# mix_pass_b head loop: batch all 64 loads of 4 heads up front, counted vmcnt per head (was one round trip per load group)
# speedup vs baseline: 1.0261x; 1.0261x over previous
.LBB0_1497:
	s_add_u32 s48, s14, 0x33400000
	s_addc_u32 s49, s15, 0
	s_add_u32 s54, s14, 0x33401000
	s_addc_u32 s55, s15, 0
	s_add_u32 s58, s14, 0x33402000
	s_addc_u32 s59, s15, 0
	v_lshl_add_u64 v[88:89], v[44:45], 0, s[48:49]
	v_lshl_add_u64 v[90:91], v[44:45], 0, s[54:55]
	v_lshl_add_u64 v[92:93], v[44:45], 0, s[58:59]
	s_add_u32 s60, s14, 0x1000
	s_addc_u32 s61, s15, 0
	s_add_u32 s70, s14, 0x2000
	s_addc_u32 s71, s15, 0
	v_lshl_add_u64 v[100:101], v[42:43], 0, s[14:15]
	v_lshl_add_u64 v[102:103], v[42:43], 0, s[60:61]
	v_lshl_add_u64 v[106:107], v[42:43], 0, s[70:71]
	v_lshl_add_u64 v[108:109], v[52:53], 0, s[14:15]
	s_add_u32 s92, s14, 0x412c0000
	s_addc_u32 s93, s15, 0
	s_add_u32 s94, s14, 0x412c1000
	s_addc_u32 s95, s15, 0
	v_lshl_add_u64 v[110:111], v[38:39], 0, s[92:93]
	v_lshl_add_u64 v[112:113], v[38:39], 0, s[94:95]
	v_lshl_add_u64 v[114:115], v[40:41], 0, s[14:15]
	v_lshl_add_u64 v[116:117], v[50:51], 0, s[14:15]
	v_lshl_add_u64 v[118:119], v[48:49], 0, s[14:15]
	v_lshl_add_u64 v[120:121], v[46:47], 0, s[14:15]
	s_and_b64 vcc, exec, s[24:25]
	s_cbranch_vccz .Lpb_zpnull
	v_lshl_add_u64 v[94:95], v[2:3], 0, s[14:15]
	v_lshl_add_u64 v[96:97], v[2:3], 0, s[60:61]
	v_lshl_add_u64 v[98:99], v[2:3], 0, s[70:71]
	s_branch .Lpb_zpdone
.Lpb_zpnull:
	v_mov_b64_e32 v[94:95], v[88:89]
	v_mov_b64_e32 v[96:97], v[90:91]
	v_mov_b64_e32 v[98:99], v[92:93]
.Lpb_zpdone:
	global_load_dword v130, v[88:89], off
	global_load_dword v131, v[90:91], off
	global_load_dword v132, v[92:93], off
	global_load_dword v133, v[94:95], off
	global_load_dword v134, v[96:97], off
	global_load_dword v135, v[98:99], off
	global_load_dword v140, v[110:111], off
	global_load_dword v141, v[112:113], off
	global_load_dword v136, v[100:101], off
	global_load_dword v137, v[102:103], off
	global_load_dword v138, v[106:107], off
	global_load_dword v139, v[108:109], off
	global_load_dword v142, v[114:115], off
	global_load_dword v143, v[116:117], off
	global_load_dword v144, v[118:119], off
	global_load_dword v145, v[120:121], off
	global_load_dword v146, v[88:89], off offset:256
	global_load_dword v147, v[90:91], off offset:256
	global_load_dword v148, v[92:93], off offset:256
	global_load_dword v149, v[94:95], off offset:256
	global_load_dword v150, v[96:97], off offset:256
	global_load_dword v151, v[98:99], off offset:256
	global_load_dword v156, v[110:111], off offset:256
	global_load_dword v157, v[112:113], off offset:256
	global_load_dword v152, v[100:101], off offset:256
	global_load_dword v153, v[102:103], off offset:256
	global_load_dword v154, v[106:107], off offset:256
	global_load_dword v155, v[108:109], off offset:256
	global_load_dword v158, v[114:115], off offset:256
	global_load_dword v159, v[116:117], off offset:256
	global_load_dword v160, v[118:119], off offset:256
	global_load_dword v161, v[120:121], off offset:256
	global_load_dword v174, v[88:89], off offset:512
	global_load_dword v175, v[90:91], off offset:512
	global_load_dword v176, v[92:93], off offset:512
	global_load_dword v177, v[94:95], off offset:512
	global_load_dword v178, v[96:97], off offset:512
	global_load_dword v179, v[98:99], off offset:512
	global_load_dword v184, v[110:111], off offset:512
	global_load_dword v185, v[112:113], off offset:512
	global_load_dword v180, v[100:101], off offset:512
	global_load_dword v181, v[102:103], off offset:512
	global_load_dword v182, v[106:107], off offset:512
	global_load_dword v183, v[108:109], off offset:512
	global_load_dword v186, v[114:115], off offset:512
	global_load_dword v187, v[116:117], off offset:512
	global_load_dword v188, v[118:119], off offset:512
	global_load_dword v189, v[120:121], off offset:512
	global_load_dword v217, v[88:89], off offset:768
	global_load_dword v218, v[90:91], off offset:768
	global_load_dword v219, v[92:93], off offset:768
	global_load_dword v220, v[94:95], off offset:768
	global_load_dword v221, v[96:97], off offset:768
	global_load_dword v222, v[98:99], off offset:768
	global_load_dword v227, v[110:111], off offset:768
	global_load_dword v228, v[112:113], off offset:768
	global_load_dword v223, v[100:101], off offset:768
	global_load_dword v224, v[102:103], off offset:768
	global_load_dword v225, v[106:107], off offset:768
	global_load_dword v226, v[108:109], off offset:768
	global_load_dword v229, v[114:115], off offset:768
	global_load_dword v230, v[116:117], off offset:768
	global_load_dword v231, v[118:119], off offset:768
	global_load_dword v232, v[120:121], off offset:768
	s_waitcnt vmcnt(48)
	v_cndmask_b32_e64 v133, 0, v133, s[24:25]
	v_cndmask_b32_e64 v134, 0, v134, s[24:25]
	v_cndmask_b32_e64 v135, 0, v135, s[24:25]
	v_sub_f32_e32 v133, v133, v130
	v_sub_f32_e32 v134, v134, v131
	v_fmac_f32_e32 v130, v133, v136
	v_fmac_f32_e32 v131, v134, v137
	v_add_f32_e32 v54, v142, v141
	v_mul_f32_e32 v54, 0xbfb8aa3b, v54
	v_exp_f32_e32 v54, v54
	v_mul_f32_e32 v56, v131, v143
	v_mul_f32_e32 v59, v56, v56
	v_add_f32_e32 v54, 1.0, v54
	v_rcp_f32_e32 v54, v54
	v_mov_b32_dpp v59, v59 quad_perm:[1,0,3,2] row_mask:0xf bank_mask:0xf bound_ctrl:1
	v_fmac_f32_e32 v59, v56, v56
	s_nop 1
	v_add_f32_dpp v59, v59, v59 quad_perm:[2,3,0,1] row_mask:0xf bank_mask:0xf bound_ctrl:1
	s_nop 1
	v_add_f32_dpp v59, v59, v59 row_half_mirror row_mask:0xf bank_mask:0xf bound_ctrl:1
	s_nop 1
	v_add_f32_dpp v59, v59, v59 row_mirror row_mask:0xf bank_mask:0xf bound_ctrl:1
	s_nop 0
	v_readlane_b32 s4, v59, 0
	v_readlane_b32 s5, v59, 16
	v_readlane_b32 s2, v59, 32
	v_readlane_b32 s3, v59, 48
	v_add_f32_e32 v59, -1.0, v54
	v_fma_f32 v59, v59, v144, 1.0
	v_mul_f32_e32 v131, v131, v59
	v_mul_f32_e32 v59, v130, v131
	v_mul_f32_e32 v61, v145, v59
	s_nop 1
	v_mov_b32_dpp v61, v61 quad_perm:[1,0,3,2] row_mask:0xf bank_mask:0xf bound_ctrl:1
	v_fmac_f32_e32 v61, v145, v59
	s_nop 1
	v_add_f32_dpp v59, v61, v61 quad_perm:[2,3,0,1] row_mask:0xf bank_mask:0xf bound_ctrl:1
	s_nop 1
	v_add_f32_dpp v59, v59, v59 row_half_mirror row_mask:0xf bank_mask:0xf bound_ctrl:1
	s_nop 1
	v_add_f32_dpp v59, v59, v59 row_mirror row_mask:0xf bank_mask:0xf bound_ctrl:1
	s_nop 0
	v_readlane_b32 s18, v59, 0
	v_readlane_b32 s33, v59, 16
	v_readlane_b32 s19, v59, 32
	v_readlane_b32 s46, v59, 48
	s_and_b64 vcc, exec, s[12:13]
	s_cbranch_vccz .Lpb_smp0
	s_add_i32 s10, s44, s45
	s_ashr_i32 s11, s10, 31
	s_lshl_b64 s[10:11], s[10:11], 11
	s_or_b32 s10, s10, s43
	s_mulk_i32 s11, 0x180
	s_mul_hi_u32 s34, s10, 0x180
	s_add_i32 s35, s34, s11
	s_mul_i32 s34, s10, 0x180
	s_branch .Lpb_adr0
.Lpb_smp0:
	s_add_u32 s34, s26, 0xffffdc00
	s_addc_u32 s35, s27, -1
.Lpb_adr0:
	v_add_f32_e32 v55, v139, v140
	v_mul_f32_e32 v57, 0xbfb8aa3b, v55
	v_exp_f32_e32 v57, v57
	v_sub_f32_e32 v135, v135, v132
	v_fmac_f32_e32 v132, v135, v138
	v_add_f32_e32 v57, 1.0, v57
	v_cmp_gt_f32_e32 vcc, s53, v57
	s_nop 1
	v_cndmask_b32_e64 v59, 0, 32, vcc
	v_ldexp_f32 v57, v57, v59
	v_log_f32_e32 v57, v57
	v_cndmask_b32_e32 v60, 0, v211, vcc
	v_mov_b32_e32 v59, s5
	v_mul_f32_e32 v61, 0x3f317217, v57
	v_fma_f32 v61, v57, s96, -v61
	v_fmac_f32_e32 v61, 0x3377d1cf, v57
	v_fmac_f32_e32 v61, 0x3f317217, v57
	v_cmp_lt_f32_e64 vcc, |v57|, s65
	s_nop 1
	v_cndmask_b32_e32 v57, v57, v61, vcc
	v_sub_f32_e32 v57, v57, v60
	v_cmp_gt_f32_e32 vcc, s56, v55
	s_nop 1
	v_cndmask_b32_e64 v55, v57, -v55, vcc
	v_sub_f32_e32 v55, -0.5, v55
	v_mul_f32_e32 v55, 0x3fb8aa3b, v55
	v_add_f32_e32 v57, s4, v59
	v_mov_b32_e32 v59, s3
	v_exp_f32_e32 v55, v55
	v_add_f32_e32 v59, s2, v59
	v_add_f32_e32 v57, v57, v59
	v_max_f32_e32 v57, 0x179abe15, v57
	v_rsq_f32_e32 v57, v57
	v_mul_f32_e32 v24, 0xbfb8aa3b, v55
	v_exp_f32_e32 v55, v24
	v_lshl_add_u64 v[24:25], s[34:35], 2, v[26:27]
	v_mul_f32_e32 v56, v56, v57
	global_store_dword v[24:25], v130, off
	global_store_dword v[24:25], v55, off offset:256
	global_store_dword v[24:25], v131, off offset:512
	global_store_dword v[24:25], v56, off offset:768
	v_mul_f32_e64 v22, v56, -v54
	global_store_dword v[24:25], v22, off offset:1024
	global_store_dword v[24:25], v132, off offset:1280
	s_and_saveexec_b64 s[30:31], s[6:7]
	s_cbranch_execz .Lpb_nobon0
	v_mov_b32_e32 v22, s33
	v_mov_b32_e32 v23, s46
	v_add_f32_e32 v22, s18, v22
	v_add_f32_e32 v23, s19, v23
	v_add_f32_e32 v22, v22, v23
	global_store_dword v1, v22, s[28:29] offset:-12
.Lpb_nobon0:
	s_or_b64 exec, exec, s[30:31]
	s_waitcnt vmcnt(38)
	v_cndmask_b32_e64 v149, 0, v149, s[24:25]
	v_cndmask_b32_e64 v150, 0, v150, s[24:25]
	v_cndmask_b32_e64 v151, 0, v151, s[24:25]
	v_sub_f32_e32 v149, v149, v146
	v_sub_f32_e32 v150, v150, v147
	v_fmac_f32_e32 v146, v149, v152
	v_fmac_f32_e32 v147, v150, v153
	v_add_f32_e32 v54, v158, v157
	v_mul_f32_e32 v54, 0xbfb8aa3b, v54
	v_exp_f32_e32 v54, v54
	v_mul_f32_e32 v56, v147, v159
	v_mul_f32_e32 v59, v56, v56
	v_add_f32_e32 v54, 1.0, v54
	v_rcp_f32_e32 v54, v54
	v_mov_b32_dpp v59, v59 quad_perm:[1,0,3,2] row_mask:0xf bank_mask:0xf bound_ctrl:1
	v_fmac_f32_e32 v59, v56, v56
	s_nop 1
	v_add_f32_dpp v59, v59, v59 quad_perm:[2,3,0,1] row_mask:0xf bank_mask:0xf bound_ctrl:1
	s_nop 1
	v_add_f32_dpp v59, v59, v59 row_half_mirror row_mask:0xf bank_mask:0xf bound_ctrl:1
	s_nop 1
	v_add_f32_dpp v59, v59, v59 row_mirror row_mask:0xf bank_mask:0xf bound_ctrl:1
	s_nop 0
	v_readlane_b32 s4, v59, 0
	v_readlane_b32 s5, v59, 16
	v_readlane_b32 s2, v59, 32
	v_readlane_b32 s3, v59, 48
	v_add_f32_e32 v59, -1.0, v54
	v_fma_f32 v59, v59, v160, 1.0
	v_mul_f32_e32 v147, v147, v59
	v_mul_f32_e32 v59, v146, v147
	v_mul_f32_e32 v61, v161, v59
	s_nop 1
	v_mov_b32_dpp v61, v61 quad_perm:[1,0,3,2] row_mask:0xf bank_mask:0xf bound_ctrl:1
	v_fmac_f32_e32 v61, v161, v59
	s_nop 1
	v_add_f32_dpp v59, v61, v61 quad_perm:[2,3,0,1] row_mask:0xf bank_mask:0xf bound_ctrl:1
	s_nop 1
	v_add_f32_dpp v59, v59, v59 row_half_mirror row_mask:0xf bank_mask:0xf bound_ctrl:1
	s_nop 1
	v_add_f32_dpp v59, v59, v59 row_mirror row_mask:0xf bank_mask:0xf bound_ctrl:1
	s_nop 0
	v_readlane_b32 s18, v59, 0
	v_readlane_b32 s33, v59, 16
	v_readlane_b32 s19, v59, 32
	v_readlane_b32 s46, v59, 48
	s_and_b64 vcc, exec, s[12:13]
	s_cbranch_vccz .Lpb_smp1
	s_add_i32 s10, s44, s45
	s_add_i32 s10, s10, 1
	s_ashr_i32 s11, s10, 31
	s_lshl_b64 s[10:11], s[10:11], 11
	s_or_b32 s10, s10, s43
	s_mulk_i32 s11, 0x180
	s_mul_hi_u32 s34, s10, 0x180
	s_add_i32 s35, s34, s11
	s_mul_i32 s34, s10, 0x180
	s_branch .Lpb_adr1
.Lpb_smp1:
	s_add_u32 s34, s26, 0xffffe800
	s_addc_u32 s35, s27, -1
.Lpb_adr1:
	v_add_f32_e32 v55, v155, v156
	v_mul_f32_e32 v57, 0xbfb8aa3b, v55
	v_exp_f32_e32 v57, v57
	v_sub_f32_e32 v151, v151, v148
	v_fmac_f32_e32 v148, v151, v154
	v_add_f32_e32 v57, 1.0, v57
	v_cmp_gt_f32_e32 vcc, s53, v57
	s_nop 1
	v_cndmask_b32_e64 v59, 0, 32, vcc
	v_ldexp_f32 v57, v57, v59
	v_log_f32_e32 v57, v57
	v_cndmask_b32_e32 v60, 0, v211, vcc
	v_mov_b32_e32 v59, s5
	v_mul_f32_e32 v61, 0x3f317217, v57
	v_fma_f32 v61, v57, s96, -v61
	v_fmac_f32_e32 v61, 0x3377d1cf, v57
	v_fmac_f32_e32 v61, 0x3f317217, v57
	v_cmp_lt_f32_e64 vcc, |v57|, s65
	s_nop 1
	v_cndmask_b32_e32 v57, v57, v61, vcc
	v_sub_f32_e32 v57, v57, v60
	v_cmp_gt_f32_e32 vcc, s56, v55
	s_nop 1
	v_cndmask_b32_e64 v55, v57, -v55, vcc
	v_sub_f32_e32 v55, -0.5, v55
	v_mul_f32_e32 v55, 0x3fb8aa3b, v55
	v_add_f32_e32 v57, s4, v59
	v_mov_b32_e32 v59, s3
	v_exp_f32_e32 v55, v55
	v_add_f32_e32 v59, s2, v59
	v_add_f32_e32 v57, v57, v59
	v_max_f32_e32 v57, 0x179abe15, v57
	v_rsq_f32_e32 v57, v57
	v_mul_f32_e32 v24, 0xbfb8aa3b, v55
	v_exp_f32_e32 v55, v24
	v_lshl_add_u64 v[24:25], s[34:35], 2, v[26:27]
	v_mul_f32_e32 v56, v56, v57
	global_store_dword v[24:25], v146, off
	global_store_dword v[24:25], v55, off offset:256
	global_store_dword v[24:25], v147, off offset:512
	global_store_dword v[24:25], v56, off offset:768
	v_mul_f32_e64 v22, v56, -v54
	global_store_dword v[24:25], v22, off offset:1024
	global_store_dword v[24:25], v148, off offset:1280
	s_and_saveexec_b64 s[30:31], s[6:7]
	s_cbranch_execz .Lpb_nobon1
	v_mov_b32_e32 v22, s33
	v_mov_b32_e32 v23, s46
	v_add_f32_e32 v22, s18, v22
	v_add_f32_e32 v23, s19, v23
	v_add_f32_e32 v22, v22, v23
	global_store_dword v1, v22, s[28:29] offset:-8
.Lpb_nobon1:
	s_or_b64 exec, exec, s[30:31]
	s_waitcnt vmcnt(28)
	v_cndmask_b32_e64 v177, 0, v177, s[24:25]
	v_cndmask_b32_e64 v178, 0, v178, s[24:25]
	v_cndmask_b32_e64 v179, 0, v179, s[24:25]
	v_sub_f32_e32 v177, v177, v174
	v_sub_f32_e32 v178, v178, v175
	v_fmac_f32_e32 v174, v177, v180
	v_fmac_f32_e32 v175, v178, v181
	v_add_f32_e32 v54, v186, v185
	v_mul_f32_e32 v54, 0xbfb8aa3b, v54
	v_exp_f32_e32 v54, v54
	v_mul_f32_e32 v56, v175, v187
	v_mul_f32_e32 v59, v56, v56
	v_add_f32_e32 v54, 1.0, v54
	v_rcp_f32_e32 v54, v54
	v_mov_b32_dpp v59, v59 quad_perm:[1,0,3,2] row_mask:0xf bank_mask:0xf bound_ctrl:1
	v_fmac_f32_e32 v59, v56, v56
	s_nop 1
	v_add_f32_dpp v59, v59, v59 quad_perm:[2,3,0,1] row_mask:0xf bank_mask:0xf bound_ctrl:1
	s_nop 1
	v_add_f32_dpp v59, v59, v59 row_half_mirror row_mask:0xf bank_mask:0xf bound_ctrl:1
	s_nop 1
	v_add_f32_dpp v59, v59, v59 row_mirror row_mask:0xf bank_mask:0xf bound_ctrl:1
	s_nop 0
	v_readlane_b32 s4, v59, 0
	v_readlane_b32 s5, v59, 16
	v_readlane_b32 s2, v59, 32
	v_readlane_b32 s3, v59, 48
	v_add_f32_e32 v59, -1.0, v54
	v_fma_f32 v59, v59, v188, 1.0
	v_mul_f32_e32 v175, v175, v59
	v_mul_f32_e32 v59, v174, v175
	v_mul_f32_e32 v61, v189, v59
	s_nop 1
	v_mov_b32_dpp v61, v61 quad_perm:[1,0,3,2] row_mask:0xf bank_mask:0xf bound_ctrl:1
	v_fmac_f32_e32 v61, v189, v59
	s_nop 1
	v_add_f32_dpp v59, v61, v61 quad_perm:[2,3,0,1] row_mask:0xf bank_mask:0xf bound_ctrl:1
	s_nop 1
	v_add_f32_dpp v59, v59, v59 row_half_mirror row_mask:0xf bank_mask:0xf bound_ctrl:1
	s_nop 1
	v_add_f32_dpp v59, v59, v59 row_mirror row_mask:0xf bank_mask:0xf bound_ctrl:1
	s_nop 0
	v_readlane_b32 s18, v59, 0
	v_readlane_b32 s33, v59, 16
	v_readlane_b32 s19, v59, 32
	v_readlane_b32 s46, v59, 48
	s_and_b64 vcc, exec, s[12:13]
	s_cbranch_vccz .Lpb_smp2
	s_add_i32 s10, s44, s45
	s_add_i32 s10, s10, 2
	s_ashr_i32 s11, s10, 31
	s_lshl_b64 s[10:11], s[10:11], 11
	s_or_b32 s10, s10, s43
	s_mulk_i32 s11, 0x180
	s_mul_hi_u32 s34, s10, 0x180
	s_add_i32 s35, s34, s11
	s_mul_i32 s34, s10, 0x180
	s_branch .Lpb_adr2
.Lpb_smp2:
	s_add_u32 s34, s26, 0xfffff400
	s_addc_u32 s35, s27, -1
.Lpb_adr2:
	v_add_f32_e32 v55, v183, v184
	v_mul_f32_e32 v57, 0xbfb8aa3b, v55
	v_exp_f32_e32 v57, v57
	v_sub_f32_e32 v179, v179, v176
	v_fmac_f32_e32 v176, v179, v182
	v_add_f32_e32 v57, 1.0, v57
	v_cmp_gt_f32_e32 vcc, s53, v57
	s_nop 1
	v_cndmask_b32_e64 v59, 0, 32, vcc
	v_ldexp_f32 v57, v57, v59
	v_log_f32_e32 v57, v57
	v_cndmask_b32_e32 v60, 0, v211, vcc
	v_mov_b32_e32 v59, s5
	v_mul_f32_e32 v61, 0x3f317217, v57
	v_fma_f32 v61, v57, s96, -v61
	v_fmac_f32_e32 v61, 0x3377d1cf, v57
	v_fmac_f32_e32 v61, 0x3f317217, v57
	v_cmp_lt_f32_e64 vcc, |v57|, s65
	s_nop 1
	v_cndmask_b32_e32 v57, v57, v61, vcc
	v_sub_f32_e32 v57, v57, v60
	v_cmp_gt_f32_e32 vcc, s56, v55
	s_nop 1
	v_cndmask_b32_e64 v55, v57, -v55, vcc
	v_sub_f32_e32 v55, -0.5, v55
	v_mul_f32_e32 v55, 0x3fb8aa3b, v55
	v_add_f32_e32 v57, s4, v59
	v_mov_b32_e32 v59, s3
	v_exp_f32_e32 v55, v55
	v_add_f32_e32 v59, s2, v59
	v_add_f32_e32 v57, v57, v59
	v_max_f32_e32 v57, 0x179abe15, v57
	v_rsq_f32_e32 v57, v57
	v_mul_f32_e32 v24, 0xbfb8aa3b, v55
	v_exp_f32_e32 v55, v24
	v_lshl_add_u64 v[24:25], s[34:35], 2, v[26:27]
	v_mul_f32_e32 v56, v56, v57
	global_store_dword v[24:25], v174, off
	global_store_dword v[24:25], v55, off offset:256
	global_store_dword v[24:25], v175, off offset:512
	global_store_dword v[24:25], v56, off offset:768
	v_mul_f32_e64 v22, v56, -v54
	global_store_dword v[24:25], v22, off offset:1024
	global_store_dword v[24:25], v176, off offset:1280
	s_and_saveexec_b64 s[30:31], s[6:7]
	s_cbranch_execz .Lpb_nobon2
	v_mov_b32_e32 v22, s33
	v_mov_b32_e32 v23, s46
	v_add_f32_e32 v22, s18, v22
	v_add_f32_e32 v23, s19, v23
	v_add_f32_e32 v22, v22, v23
	global_store_dword v1, v22, s[28:29] offset:-4
.Lpb_nobon2:
	s_or_b64 exec, exec, s[30:31]
	s_waitcnt vmcnt(18)
	v_cndmask_b32_e64 v220, 0, v220, s[24:25]
	v_cndmask_b32_e64 v221, 0, v221, s[24:25]
	v_cndmask_b32_e64 v222, 0, v222, s[24:25]
	v_sub_f32_e32 v220, v220, v217
	v_sub_f32_e32 v221, v221, v218
	v_fmac_f32_e32 v217, v220, v223
	v_fmac_f32_e32 v218, v221, v224
	v_add_f32_e32 v54, v229, v228
	v_mul_f32_e32 v54, 0xbfb8aa3b, v54
	v_exp_f32_e32 v54, v54
	v_mul_f32_e32 v56, v218, v230
	v_mul_f32_e32 v59, v56, v56
	v_add_f32_e32 v54, 1.0, v54
	v_rcp_f32_e32 v54, v54
	v_mov_b32_dpp v59, v59 quad_perm:[1,0,3,2] row_mask:0xf bank_mask:0xf bound_ctrl:1
	v_fmac_f32_e32 v59, v56, v56
	s_nop 1
	v_add_f32_dpp v59, v59, v59 quad_perm:[2,3,0,1] row_mask:0xf bank_mask:0xf bound_ctrl:1
	s_nop 1
	v_add_f32_dpp v59, v59, v59 row_half_mirror row_mask:0xf bank_mask:0xf bound_ctrl:1
	s_nop 1
	v_add_f32_dpp v59, v59, v59 row_mirror row_mask:0xf bank_mask:0xf bound_ctrl:1
	s_nop 0
	v_readlane_b32 s4, v59, 0
	v_readlane_b32 s5, v59, 16
	v_readlane_b32 s2, v59, 32
	v_readlane_b32 s3, v59, 48
	v_add_f32_e32 v59, -1.0, v54
	v_fma_f32 v59, v59, v231, 1.0
	v_mul_f32_e32 v218, v218, v59
	v_mul_f32_e32 v59, v217, v218
	v_mul_f32_e32 v61, v232, v59
	s_nop 1
	v_mov_b32_dpp v61, v61 quad_perm:[1,0,3,2] row_mask:0xf bank_mask:0xf bound_ctrl:1
	v_fmac_f32_e32 v61, v232, v59
	s_nop 1
	v_add_f32_dpp v59, v61, v61 quad_perm:[2,3,0,1] row_mask:0xf bank_mask:0xf bound_ctrl:1
	s_nop 1
	v_add_f32_dpp v59, v59, v59 row_half_mirror row_mask:0xf bank_mask:0xf bound_ctrl:1
	s_nop 1
	v_add_f32_dpp v59, v59, v59 row_mirror row_mask:0xf bank_mask:0xf bound_ctrl:1
	s_nop 0
	v_readlane_b32 s18, v59, 0
	v_readlane_b32 s33, v59, 16
	v_readlane_b32 s19, v59, 32
	v_readlane_b32 s46, v59, 48
	s_and_b64 vcc, exec, s[12:13]
	s_cbranch_vccz .Lpb_smp3
	s_add_i32 s10, s44, s45
	s_add_i32 s10, s10, 3
	s_ashr_i32 s11, s10, 31
	s_lshl_b64 s[10:11], s[10:11], 11
	s_or_b32 s10, s10, s43
	s_mulk_i32 s11, 0x180
	s_mul_hi_u32 s34, s10, 0x180
	s_add_i32 s35, s34, s11
	s_mul_i32 s34, s10, 0x180
	s_branch .Lpb_adr3
.Lpb_smp3:
	s_mov_b64 s[34:35], s[26:27]
.Lpb_adr3:
	v_add_f32_e32 v55, v226, v227
	v_mul_f32_e32 v57, 0xbfb8aa3b, v55
	v_exp_f32_e32 v57, v57
	v_sub_f32_e32 v222, v222, v219
	v_fmac_f32_e32 v219, v222, v225
	v_add_f32_e32 v57, 1.0, v57
	v_cmp_gt_f32_e32 vcc, s53, v57
	s_nop 1
	v_cndmask_b32_e64 v59, 0, 32, vcc
	v_ldexp_f32 v57, v57, v59
	v_log_f32_e32 v57, v57
	v_cndmask_b32_e32 v60, 0, v211, vcc
	v_mov_b32_e32 v59, s5
	v_mul_f32_e32 v61, 0x3f317217, v57
	v_fma_f32 v61, v57, s96, -v61
	v_fmac_f32_e32 v61, 0x3377d1cf, v57
	v_fmac_f32_e32 v61, 0x3f317217, v57
	v_cmp_lt_f32_e64 vcc, |v57|, s65
	s_nop 1
	v_cndmask_b32_e32 v57, v57, v61, vcc
	v_sub_f32_e32 v57, v57, v60
	v_cmp_gt_f32_e32 vcc, s56, v55
	s_nop 1
	v_cndmask_b32_e64 v55, v57, -v55, vcc
	v_sub_f32_e32 v55, -0.5, v55
	v_mul_f32_e32 v55, 0x3fb8aa3b, v55
	v_add_f32_e32 v57, s4, v59
	v_mov_b32_e32 v59, s3
	v_exp_f32_e32 v55, v55
	v_add_f32_e32 v59, s2, v59
	v_add_f32_e32 v57, v57, v59
	v_max_f32_e32 v57, 0x179abe15, v57
	v_rsq_f32_e32 v57, v57
	v_mul_f32_e32 v24, 0xbfb8aa3b, v55
	v_exp_f32_e32 v55, v24
	v_lshl_add_u64 v[24:25], s[34:35], 2, v[26:27]
	v_mul_f32_e32 v56, v56, v57
	global_store_dword v[24:25], v217, off
	global_store_dword v[24:25], v55, off offset:256
	global_store_dword v[24:25], v218, off offset:512
	global_store_dword v[24:25], v56, off offset:768
	v_mul_f32_e64 v22, v56, -v54
	global_store_dword v[24:25], v22, off offset:1024
	global_store_dword v[24:25], v219, off offset:1280
	s_and_saveexec_b64 s[8:9], s[6:7]
	s_cbranch_execz .LBB0_1496
	v_mov_b32_e32 v22, s33
	v_mov_b32_e32 v23, s46
	v_add_f32_e32 v22, s18, v22
	v_add_f32_e32 v23, s19, v23
	v_add_f32_e32 v22, v22, v23
	global_store_dword v1, v22, s[28:29]
	s_branch .LBB0_1496
